# P5 balance step 2: sample-row waves keep 2 prompt rows; their 3rd row goes to waves 4,5 and 4th to waves 2,3 (heaviest wave 5.0 row units)
# speedup vs baseline: 1.0104x; 1.0058x over previous
; __device__ __forceinline__ void p5_final_norm(Frame& F, float* dst, const f32x4 (&xpre)[16]) {
;     const int gw = F.vcu * NWAVES + F.wave, NGW = F.G * NWAVES;
;     for (int r = F.wave * F.G + F.vcu; r < MS; r += NGW) p5_row<true>(F, MP + r, dst);
;     if (gw < MP) p5_row<false, true>(F, gw, dst, xpre);
;     for (int m = gw + NGW; m < MP; m += NGW) p5_row<false>(F, m, dst);
.LBB0_840:
	s_add_i32 s0, s12, s28
	s_cmpk_gt_i32 s0, 0x1fff
	s_cbranch_scc1 .LBB0_843
	s_mov_b32 s100, 0
	s_movk_i32 s99, 0x2000
	s_cmp_lt_u32 s33, 2
	s_cselect_b32 s99, 0x1000, s99
	s_add_i32 s3, s3, s2
	s_lshl_b32 s1, s3, 3
	s_add_i32 s22, s33, s1
	s_ashr_i32 s1, s0, 31
	s_lshl_b64 s[2:3], s[0:1], 13
	v_mov_b32_e32 v131, 0
	s_waitcnt lgkmcnt(0)
	s_add_u32 s2, s10, s2
	v_mov_b32_e32 v1, v131
	s_addc_u32 s3, s11, s3
	v_lshl_add_u64 v[0:1], s[2:3], 0, v[0:1]
	s_mov_b64 s[2:3], 0x17200000
	s_ashr_i32 s29, s28, 31
	v_lshl_add_u64 v[94:95], v[0:1], 0, s[2:3]
	s_lshl_b64 s[2:3], s[28:29], 13
	s_lshl_b64 s[0:1], s[0:1], 14
	s_add_u32 s6, s6, s0
	s_addc_u32 s7, s7, s1
	s_lshl_b64 s[10:11], s[28:29], 14
	v_lshl_add_u64 v[80:81], s[4:5], 0, v[130:131]
	s_mov_b64 s[4:5], 0x1000
	s_mov_b64 s[12:13], 0x1800
	s_mov_b64 s[14:15], 0x2000
	s_mov_b64 s[16:17], 0x2800
	s_mov_b64 s[18:19], 0x3000
	s_mov_b64 s[20:21], 0x3800
	s_add_u32 s8, s8, s0
	v_lshl_add_u64 v[82:83], v[80:81], 0, s[4:5]
	v_lshl_add_u64 v[84:85], v[80:81], 0, s[12:13]
	v_lshl_add_u64 v[86:87], v[80:81], 0, s[14:15]
	v_lshl_add_u64 v[88:89], v[80:81], 0, s[16:17]
	v_lshl_add_u64 v[90:91], v[80:81], 0, s[18:19]
	v_lshl_add_u64 v[92:93], v[80:81], 0, s[20:21]
	s_addc_u32 s9, s9, s1
	s_movk_i32 s23, 0x1000
	s_movk_i32 s24, 0x2000
	s_movk_i32 s25, 0x3000
	v_mov_b32_e32 v106, 0x358637bd
	v_mov_b32_e32 v107, 0x39800000
	s_mov_b32 s26, 0xf800000
	v_mov_b32_e32 v108, 0x260

; __device__ __forceinline__ void p5_final_norm(Frame& F, float* dst, const f32x4 (&xpre)[16]) {
;     ...
;     for (int r = F.wave * F.G + F.vcu; r < MS; r += NGW) p5_row<true>(F, MP + r, dst);
;     if (gw < MP) p5_row<false, true>(F, gw, dst, xpre);
;     for (int m = gw + NGW; m < MP; m += NGW) p5_row<false>(F, m, dst);
.LBB0_843:
	s_cmp_eq_u32 s100, 1
	s_cbranch_scc1 .Lp5_end
	s_mov_b32 s100, 1
	s_sub_u32 s101, s33, 2
	s_cmp_lt_u32 s101, 2
	s_cbranch_scc0 .Lp5_b
	s_sub_u32 s6, s6, 0x2008000
	s_subb_u32 s7, s7, 0
	s_sub_u32 s8, s8, 0x2008000
	s_subb_u32 s9, s9, 0
	v_subrev_co_u32_e32 v94, vcc, 0x1004000, v94
	s_nop 1
	v_subbrev_co_u32_e32 v95, vcc, 0, v95, vcc
	s_branch .Lp5_go
.Lp5_b:
	s_sub_u32 s101, s33, 4
	s_cmp_lt_u32 s101, 2
	s_cbranch_scc0 .Lp5_end
	s_sub_u32 s6, s6, 0x4010000
	s_subb_u32 s7, s7, 0
	s_sub_u32 s8, s8, 0x4010000
	s_subb_u32 s9, s9, 0
	v_subrev_co_u32_e32 v94, vcc, 0x2008000, v94
	s_nop 1
	v_subbrev_co_u32_e32 v95, vcc, 0, v95, vcc
.Lp5_go:
	s_mov_b32 s22, 0x7fff0000
	s_movk_i32 s99, 0x2000
	s_branch .LBB0_842
